# v037 + MLA: K-fragment LDS reads issued right after the barrier, before the next tile's DMA address math
# baseline (speedup 1.0000x reference)
.LBB0_664:
	s_barrier
	s_mul_i32 s23, s54, 0x3400
	v_add_u32_e32 v193, s23, v157
	ds_read_b128 v[2:5], v193
	ds_read_b128 v[6:9], v193 offset:32
	ds_read_b128 v[10:13], v193 offset:64
	ds_read_b128 v[160:163], v193 offset:96
	ds_read_b128 v[164:167], v193 offset:128
	ds_read_b128 v[168:171], v193 offset:160
	s_cmp_gt_u32 s60, 33
	s_cbranch_scc1 .LBB0_666
	s_cmp_lt_u32 s60, 2
	s_cselect_b32 s23, 8, 11
	s_movk_i32 s34, 0xff00
	s_cselect_b32 s34, 0x8000, s34
	s_lshl_b32 s23, s53, s23
	s_add_i32 s34, s34, s23
	s_add_i32 s34, s59, s34
	s_ashr_i32 s35, s34, 31
	s_lshl_b64 s[68:69], s[34:35], 11
	s_add_u32 s23, s1, s68
	s_addc_u32 s56, s8, s69
	s_lshl_b64 s[34:35], s[34:35], 6
	s_add_u32 s34, s39, s34
	s_addc_u32 s35, s40, s35
	s_lshl_b32 s61, s55, 13
	s_add_i32 s61, s61, 0x9c00
	s_mul_i32 s64, s55, 0x3400
	v_mov_b32_e32 v84, s35
	v_mov_b32_e32 v86, s34
	s_and_b64 s[34:35], s[16:17], exec
	v_mov_b32_e32 v85, s23
	s_cselect_b32 s23, s64, s61
	v_mov_b32_e32 v80, s56
	s_add_i32 m0, s43, s23
	v_cndmask_b32_e64 v83, v80, v84, s[26:27]
	v_cndmask_b32_e64 v82, v85, v86, s[26:27]
	s_and_b64 s[34:35], s[14:15], exec
	v_lshl_add_u64 v[82:83], v[144:145], 1, v[82:83]
	s_cselect_b32 s23, s64, s61
	global_load_lds_dwordx4 v[82:83], off
	v_cndmask_b32_e64 v83, v80, v84, s[28:29]
	v_cndmask_b32_e64 v82, v85, v86, s[28:29]
	s_add_i32 m0, s44, s23
	v_lshl_add_u64 v[82:83], v[146:147], 1, v[82:83]
	s_and_b64 s[34:35], s[24:25], exec
	global_load_lds_dwordx4 v[82:83], off
	v_cndmask_b32_e64 v83, v80, v84, s[30:31]
	v_cndmask_b32_e64 v82, v85, v86, s[30:31]
	s_cselect_b32 s23, s64, s61
	v_lshl_add_u64 v[82:83], v[148:149], 1, v[82:83]
	s_add_i32 m0, s42, s23
	s_nop 0
	global_load_lds_dwordx4 v[82:83], off
.LBB0_666:
	s_waitcnt lgkmcnt(5)
	v_mfma_f32_32x32x16_bf16 v[96:111], v[2:5], v[112:115], 0
	s_waitcnt lgkmcnt(4)
	v_mfma_f32_32x32x16_bf16 v[96:111], v[6:9], v[116:119], v[96:111]
	s_waitcnt lgkmcnt(3)
	v_mfma_f32_32x32x16_bf16 v[96:111], v[10:13], v[120:123], v[96:111]
	s_waitcnt lgkmcnt(2)
	v_mfma_f32_32x32x16_bf16 v[96:111], v[160:163], v[124:127], v[96:111]
	s_waitcnt lgkmcnt(1)
	v_mfma_f32_32x32x16_bf16 v[96:111], v[164:167], v[218:221], v[96:111]
	s_waitcnt lgkmcnt(0)
	v_mfma_f32_32x32x16_bf16 v[96:111], v[168:171], v[222:225], v[96:111]
	s_nop 7
	s_waitcnt lgkmcnt(0)
	v_mfma_f32_32x32x16_bf16 v[80:95], v[2:5], v[128:131], 0
	s_nop 1
	v_max3_f32 v0, v96, s62, v97
	v_max3_f32 v0, v0, v98, v99
	v_max3_f32 v0, v0, v100, v101
	v_max3_f32 v0, v0, v102, v103
	v_max3_f32 v0, v0, v104, v105
	v_max3_f32 v0, v0, v106, v107
	v_max3_f32 v0, v0, v108, v109
	v_max3_f32 v0, v0, v110, v111
	v_mov_b32_e32 v2, v0
	s_nop 1
	v_permlane32_swap_b32_e32 v0, v2
	v_max_f32_e32 v0, v0, v2
	v_mul_f32_e32 v0, 0x3e16c740, v0
	v_mfma_f32_32x32x16_bf16 v[80:95], v[6:9], v[132:135], v[80:95]
	v_add_f32_e32 v2, 0x41000000, v176
	v_cmp_gt_f32_e32 vcc, v0, v2
	s_nop 1
	v_cndmask_b32_e32 v196, v176, v0, vcc
	v_sub_f32_e32 v0, v176, v196
	v_fma_f32 v2, v96, s63, -v196
	v_fma_f32 v3, v97, s63, -v196
	v_fma_f32 v4, v98, s63, -v196
	v_fma_f32 v5, v99, s63, -v196
	v_fma_f32 v6, v100, s63, -v196
	v_fma_f32 v7, v101, s63, -v196
	v_fma_f32 v8, v102, s63, -v196
	v_fma_f32 v9, v103, s63, -v196
	v_fma_f32 v14, v104, s63, -v196
	v_fma_f32 v96, v105, s63, -v196
	v_mfma_f32_32x32x16_bf16 v[80:95], v[10:13], v[136:139], v[80:95]
	v_fma_f32 v97, v106, s63, -v196
	v_fma_f32 v10, v107, s63, -v196
	v_fma_f32 v11, v108, s63, -v196
	v_fma_f32 v12, v109, s63, -v196
	v_fma_f32 v13, v110, s63, -v196
	v_fma_f32 v98, v111, s63, -v196
	v_exp_f32_e32 v0, v0
	v_mfma_f32_32x32x16_bf16 v[80:95], v[160:163], v[140:143], v[80:95]
	v_exp_f32_e32 v15, v2
	v_exp_f32_e32 v162, v3
	v_exp_f32_e32 v160, v4
	v_exp_f32_e32 v163, v5
	v_exp_f32_e32 v161, v6
	v_exp_f32_e32 v172, v10
	v_exp_f32_e32 v173, v12
	v_mfma_f32_32x32x16_bf16 v[80:95], v[164:167], v[226:229], v[80:95]
	v_exp_f32_e32 v165, v7
	v_exp_f32_e32 v164, v8
	v_exp_f32_e32 v166, v9
	v_exp_f32_e32 v167, v14
	v_exp_f32_e32 v174, v98
	v_cvt_pk_bf16_f32 v104, v15, v162
	v_cvt_pk_bf16_f32 v105, v160, v163
	v_mfma_f32_32x32x16_bf16 v[80:95], v[168:171], v[244:247], v[80:95]
	v_exp_f32_e32 v171, v96
	v_exp_f32_e32 v168, v97
	v_exp_f32_e32 v169, v11
	v_exp_f32_e32 v170, v13
	v_cvt_pk_bf16_f32 v106, v161, v165
	v_cvt_pk_bf16_f32 v107, v164, v166
	v_cvt_pk_bf16_f32 v2, v167, v171
	v_cvt_pk_bf16_f32 v3, v168, v172
	v_cvt_pk_bf16_f32 v4, v169, v173
	v_cvt_pk_bf16_f32 v5, v170, v174
	v_cmp_eq_f32_e32 vcc, 1.0, v0
	s_cmp_eq_u64 vcc, exec
	s_cbranch_scc1 .LBB0_668
	v_pk_mul_f32 v[78:79], v[78:79], v[0:1] op_sel_hi:[1,0]
	v_pk_mul_f32 v[76:77], v[76:77], v[0:1] op_sel_hi:[1,0]
	v_pk_mul_f32 v[74:75], v[74:75], v[0:1] op_sel_hi:[1,0]
	v_pk_mul_f32 v[72:73], v[72:73], v[0:1] op_sel_hi:[1,0]
	v_pk_mul_f32 v[70:71], v[70:71], v[0:1] op_sel_hi:[1,0]
	v_pk_mul_f32 v[68:69], v[68:69], v[0:1] op_sel_hi:[1,0]
	v_pk_mul_f32 v[66:67], v[66:67], v[0:1] op_sel_hi:[1,0]
	v_pk_mul_f32 v[64:65], v[64:65], v[0:1] op_sel_hi:[1,0]
	v_pk_mul_f32 v[62:63], v[62:63], v[0:1] op_sel_hi:[1,0]
	v_pk_mul_f32 v[60:61], v[60:61], v[0:1] op_sel_hi:[1,0]
	v_pk_mul_f32 v[58:59], v[58:59], v[0:1] op_sel_hi:[1,0]
	v_pk_mul_f32 v[56:57], v[56:57], v[0:1] op_sel_hi:[1,0]
	v_pk_mul_f32 v[54:55], v[54:55], v[0:1] op_sel_hi:[1,0]
	v_pk_mul_f32 v[52:53], v[52:53], v[0:1] op_sel_hi:[1,0]
	v_pk_mul_f32 v[50:51], v[50:51], v[0:1] op_sel_hi:[1,0]
	v_pk_mul_f32 v[48:49], v[48:49], v[0:1] op_sel_hi:[1,0]
